# GEMM1/GEMM3 unit order: trailing single row-panel group merged into a 5-panel group (L2 locality of the last rounds on XCD 7)
# speedup vs baseline: 1.0145x; 1.0043x over previous
;     __host__ __device__ bool next(int i, Unit& u) const {
;         const long L = (long)i * G + c; if (L >= nwg) return false;
;         int wgid = (int)L; { const int q = nwg / NXCD, r = nwg % NXCD, xcd = wgid % NXCD, off = wgid / NXCD; wgid = (xcd < r ? xcd * (q + 1) : r * (q + 1) + (xcd - r) * q) + off; }
;         const int nig = WGM * nN, gid = wgid / nig, fm = gid * WGM, gsz = (nM - fm) < WGM ? (nM - fm) : WGM;
;         u.pm = fm + ((wgid % nig) % gsz); u.pn = (wgid % nig) / gsz; return true;
;     }
; template <class Epi, class Sched, bool ALIGN_EPI = false, bool SP2 = false>
; __device__ __forceinline__ void gemm_phase(PG8_LAS unsigned char* lds, const Gemm g, const Sched& S, const Epi& E) {
;     int tid_o = S.wv * 64 + lane_id_(); asm volatile("" : "+v"(tid_o));
;     const int tid = tid_o, wid = __builtin_amdgcn_readfirstlane(tid >> 6), lane = tid & 63, wr = wid >> 2, wc = wid & 3, fr = lane & 15, fq = lane >> 4;
;     const int K = g.K, nt = K / BK;
;     unsigned voffA[2], voffB[2];
; #pragma unroll
;     for (int i = 0; i < 2; ++i) { int R, C; stage_rc(tid * 16 + i * 8192, R, C); const int Rb = Epi::PERM ? ((R & ~31) + perm32(R & 31)) : R;
;         const int Ra = Epi::ROWPERM ? ((R & ~63) + 4 * (R & 15) + ((R >> 4) & 3)) : R;
;         voffA[i] = (unsigned)(Ra * (Epi::ATILED ? BK : K) + C) * 2u; voffB[i] = (unsigned)(Rb * K + C) * 2u; }
;     const size_t kstep = (size_t)(BK * 2);
;     const size_t hstep = (size_t)HALF * K * 2;
;     const size_t tstep = 2 * hstep;
;     const size_t kstepA = Epi::ATILED ? (size_t)(BM * BK * 2) : kstep, hstepA = Epi::ATILED ? (size_t)(HALF * BK * 2) : hstep;
;     const unsigned ldsw = (unsigned)wid * 1024u;
;     const int aoff = lds_byte(wr * 64 + fr, fq * 8), boff = lds_byte(wc * 32 + fr, fq * 8);
;     ...
;     Unit cur, nxt; int ui = 0;
;     if (!S.next(0, cur)) return;
;     f32x4 acc[2][2][4][2];
; #pragma unroll
;     for (int a = 0; a < 2; ++a)
; #pragma unroll
;         for (int b = 0; b < 2; ++b)
; #pragma unroll
;             for (int m = 0; m < 4; ++m)
; #pragma unroll
;                 for (int n = 0; n < 2; ++n) acc[a][b][m][n] = (f32x4){0.f, 0.f, 0.f, 0.f};
;     bf16x8 At[4][2], B0[2][2], B1[2][2];
;     const char* cA = (const char*)g.A + (size_t)cur.pm * tstep; const char* cB = (const char*)g.Bt + (size_t)cur.pn * tstep;
;     S.a_ready(cur);
;     if constexpr (SP2) {
.LBB0_101:
	s_add_u32 s92, s80, 0x37d00000
	s_addc_u32 s93, s81, 0
	s_cmp_lt_i32 s82, 2
	s_cselect_b64 s[4:5], -1, 0
	s_and_b64 s[0:1], s[4:5], s[0:1]
	s_andn2_b64 vcc, exec, s[0:1]
	v_writelane_b32 v254, s68, 61
	s_cbranch_vccnz .LBB0_140
	v_readlane_b32 s0, v254, 10
	v_mbcnt_lo_u32_b32 v0, -1, 0
	v_mbcnt_hi_u32_b32 v0, -1, v0
	s_cmpk_gt_i32 s2, 0x7dc
	s_nop 0
	v_add_u32_e32 v10, s0, v0
	s_nop 0
	v_readfirstlane_b32 s1, v10
	s_cbranch_scc1 .LBB0_128
	v_lshlrev_b32_e32 v0, 4, v10
	v_add_u32_e32 v1, 0x2000, v0
	v_ashrrev_i32_e32 v2, 31, v1
	v_lshrrev_b32_e32 v2, 22, v2
	v_add_u32_e32 v2, v1, v2
	v_ashrrev_i32_e32 v8, 10, v2
	v_mul_i32_i24_e32 v2, 0x400, v8
	v_sub_u32_e32 v1, v1, v2
	v_lshrrev_b32_e32 v2, 4, v1
	v_bitop3_b32 v1, v2, v1, 32 bitop3:0x6c
	v_ashrrev_i32_e32 v2, 31, v1
	v_lshrrev_b32_e32 v2, 26, v2
	v_add_u32_e32 v2, v1, v2
	v_lshlrev_b32_e32 v3, 3, v8
	v_ashrrev_i32_e32 v9, 6, v2
	v_and_b32_e32 v3, -16, v3
	v_add_u32_e32 v3, v9, v3
	v_and_b32_e32 v4, 3, v9
	s_mov_b32 s0, 0x7ffe0
	v_lshrrev_b32_e32 v5, 2, v3
	v_lshlrev_b32_e32 v6, 1, v3
	v_and_b32_e32 v2, 0xc0, v2
	v_and_or_b32 v4, v3, s0, v4
	v_and_b32_e32 v5, 4, v5
	v_and_b32_e32 v6, 24, v6
	v_sub_u32_e32 v1, v1, v2
	v_mov_b32_e32 v2, 1
	v_or3_b32 v4, v4, v5, v6
	v_lshlrev_b32_e32 v5, 5, v8
	v_ashrrev_i16_sdwa v1, v2, sext(v1) dst_sel:DWORD dst_unused:UNUSED_PAD src0_sel:DWORD src1_sel:BYTE_0
	v_and_b32_e32 v5, 32, v5
	v_bfe_i32 v11, v1, 0, 16
	v_add_lshl_u32 v1, v5, v11, 1
	v_lshl_add_u32 v128, v4, 13, v1
	v_lshl_add_u32 v130, v3, 13, v1
	v_bfe_i32 v1, v10, 27, 1
	v_lshrrev_b32_e32 v1, 22, v1
	v_add_u32_e32 v1, v0, v1
	v_and_b32_e32 v1, 0xfffffc00, v1
	v_sub_u32_e32 v0, v0, v1
	v_lshrrev_b32_e32 v1, 4, v0
	v_ashrrev_i32_e32 v3, 31, v10
	v_bitop3_b32 v0, v1, v0, 32 bitop3:0x6c
	v_lshrrev_b32_e32 v3, 26, v3
	v_ashrrev_i32_e32 v1, 31, v0
	v_add_u32_e32 v3, v10, v3
	v_lshrrev_b32_e32 v1, 26, v1
	v_ashrrev_i32_e32 v13, 6, v3
	v_add_u32_e32 v1, v0, v1
	v_lshlrev_b32_e32 v3, 3, v13
	s_add_u32 s3, s80, 0x100000
	v_ashrrev_i32_e32 v12, 6, v1
	v_and_b32_e32 v3, -16, v3
	s_addc_u32 s29, s81, 0
	v_add_u32_e32 v3, v12, v3
	v_and_b32_e32 v4, 3, v12
	s_ashr_i32 s52, s2, 31
	v_and_or_b32 v4, v3, s0, v4
	s_lshr_b32 s0, s52, 29
	s_add_i32 s0, s2, s0
	s_and_b32 s6, s0, -8
	s_sub_i32 s6, s2, s6
	s_ashr_i32 s13, s1, 6
	s_mul_i32 s8, s6, 0xfb
	s_ashr_i32 s12, s1, 8
	s_lshl_b32 s33, s13, 10
	s_add_i32 s8, s8, 5
	s_ashr_i32 s0, s0, 3
	s_mul_i32 s7, s6, 0xfc
	s_cmp_lt_i32 s6, 5
	s_cselect_b32 s6, s7, s8
	s_add_i32 s6, s6, s0
	s_mul_hi_i32 s0, s6, 0x4325c53f
	s_lshr_b32 s7, s0, 31
	s_ashr_i32 s0, s0, 6
	v_lshrrev_b32_e32 v5, 2, v3
	v_lshlrev_b32_e32 v6, 1, v3
	v_and_b32_e32 v1, 0xc0, v1
	s_add_i32 s0, s0, s7
	s_min_i32 s0, s0, 7
	v_and_b32_e32 v5, 4, v5
	v_and_b32_e32 v6, 24, v6
	v_sub_u32_e32 v0, v0, v1
	s_lshl_b32 s8, s0, 2
	v_or3_b32 v4, v4, v5, v6
	v_lshlrev_b32_e32 v5, 5, v13
	v_ashrrev_i16_sdwa v0, v2, sext(v0) dst_sel:DWORD dst_unused:UNUSED_PAD src0_sel:DWORD src1_sel:BYTE_0
	s_sub_i32 s7, 33, s8
	s_mulk_i32 s0, 0xf4
	v_and_b32_e32 v5, 32, v5
	v_bfe_i32 v14, v0, 0, 16
	s_cmp_eq_u32 s7, 5
	s_cselect_b32 s9, 5, 4
	s_sub_i32 s10, s6, s0
	v_add_lshl_u32 v0, v5, v14, 1
	s_sext_i32_i16 s0, s10
	v_cvt_f32_ubyte0_e32 v2, s9
	v_lshl_add_u32 v132, v4, 13, v0
	v_cvt_f32_i32_e32 v1, s0
	v_rcp_iflag_f32_e32 v4, v2
	v_lshl_add_u32 v134, v3, 13, v0
	s_ashr_i32 s0, s0, 30
	s_or_b32 s0, s0, 1
	v_mul_f32_e32 v0, v1, v4
	v_trunc_f32_e32 v0, v0
	v_fma_f32 v1, -v0, v2, v1
	v_cvt_i32_f32_e32 v0, v0
	v_cmp_ge_f32_e64 s[6:7], |v1|, v2
	s_and_b64 s[6:7], s[6:7], exec
	s_cselect_b32 s0, s0, 0
	v_readfirstlane_b32 s6, v0
	s_add_i32 s0, s6, s0
	s_mul_i32 s6, s0, s9
	s_sub_i32 s6, s10, s6
	s_sext_i32_i16 s6, s6
	s_add_i32 s30, s8, s6
	s_ashr_i32 s31, s30, 31
	s_bfe_i64 s[8:9], s[0:1], 0x100000
	s_lshl_b64 s[6:7], s[30:31], 21
	s_lshl_b64 s[8:9], s[8:9], 21
	s_add_u32 s84, s3, s8
	s_addc_u32 s85, s29, s9
	s_add_i32 s53, s33, 0
	s_add_i32 m0, s53, 0x10000
	v_mov_b32_e32 v137, 0
	global_load_lds_dwordx4 v132, s[84:85]
	s_add_i32 m0, s53, 0x12000
	s_add_u32 s8, s84, 0x100000
	global_load_lds_dwordx4 v128, s[84:85]
	s_addc_u32 s9, s85, 0
	s_add_i32 m0, s53, 0x14000
	v_mov_b32_e32 v133, v137
	global_load_lds_dwordx4 v132, s[8:9]
	s_add_i32 m0, s53, 0x16000
	s_add_u32 s34, s92, s6
	s_addc_u32 s35, s93, s7
	s_add_i32 s54, s53, 0x2000
	global_load_lds_dwordx4 v128, s[8:9]
	s_mov_b32 m0, s53
	s_add_u32 s6, s34, 0x100000
	global_load_lds_dwordx4 v134, s[34:35]
	s_mov_b32 m0, s54
	s_addc_u32 s7, s35, 0
	s_add_i32 s55, s53, 0x4000
	global_load_lds_dwordx4 v130, s[34:35]
	s_mov_b32 m0, s55
	s_add_i32 s56, s53, 0x6000
	global_load_lds_dwordx4 v134, s[6:7]
	s_mov_b32 m0, s56
	v_mov_b32_e32 v129, v137
	global_load_lds_dwordx4 v130, s[6:7]
	v_mov_b32_e32 v135, v137
	v_mov_b32_e32 v131, v137
	s_cmp_eq_u32 s12, 1
	s_mov_b32 s57, 0
	v_lshl_add_u64 v[6:7], s[84:85], 0, v[132:133]
	v_lshl_add_u64 v[4:5], s[84:85], 0, v[128:129]
	v_lshl_add_u64 v[0:1], s[34:35], 0, v[134:135]
	s_cselect_b64 s[6:7], -1, 0
	s_cmp_lg_u32 s12, 1
	v_lshl_add_u64 v[2:3], s[34:35], 0, v[130:131]
	s_cbranch_scc1 .LBB0_105
	s_barrier

;     __host__ __device__ bool next(int i, Unit& u) const {
;         const long L = (long)i * G + c; if (L >= nwg) return false;
;         int wgid = (int)L; { const int q = nwg / NXCD, r = nwg % NXCD, xcd = wgid % NXCD, off = wgid / NXCD; wgid = (xcd < r ? xcd * (q + 1) : r * (q + 1) + (xcd - r) * q) + off; }
;         const int nig = WGM * nN, gid = wgid / nig, fm = gid * WGM, gsz = (nM - fm) < WGM ? (nM - fm) : WGM;
;         u.pm = fm + ((wgid % nig) % gsz); u.pn = (wgid % nig) / gsz; return true;
;     }
.LBB0_113:
	s_ashr_i32 s18, s20, 3
	s_add_i32 s18, s22, s18
	s_mul_hi_i32 s19, s18, 0x4325c53f
	s_lshr_b32 s20, s19, 31
	s_ashr_i32 s19, s19, 6
	s_add_i32 s19, s19, s20
	s_min_i32 s19, s19, 7
	s_lshl_b32 s20, s19, 2
	s_sub_i32 s21, 33, s20
	s_cmp_eq_u32 s21, 5
	s_cselect_b32 s21, 5, 4
	s_abs_i32 s22, s21
	v_cvt_f32_u32_e32 v0, s22
	s_sub_i32 s24, 0, s22
	s_mulk_i32 s19, 0xf4
	s_sub_i32 s19, s18, s19
	v_rcp_iflag_f32_e32 v0, v0
	s_abs_i32 s18, s19
	s_xor_b32 s23, s19, s21
	s_ashr_i32 s23, s23, 31
	v_mul_f32_e32 v0, 0x4f7ffffe, v0
	v_cvt_u32_f32_e32 v0, v0
	s_nop 0
	v_readfirstlane_b32 s25, v0
	s_mul_i32 s24, s24, s25
	s_mul_hi_u32 s24, s25, s24
	s_add_i32 s25, s25, s24
	s_mul_hi_u32 s24, s18, s25
	s_mul_i32 s25, s24, s22
	s_sub_i32 s18, s18, s25
	s_add_i32 s27, s24, 1
	s_sub_i32 s25, s18, s22
	s_cmp_ge_u32 s18, s22
	s_cselect_b32 s24, s27, s24
	s_cselect_b32 s18, s25, s18
	s_add_i32 s25, s24, 1
	s_cmp_ge_u32 s18, s22
	s_cselect_b32 s18, s25, s24
	s_xor_b32 s18, s18, s23
	s_sub_i32 s18, s18, s23
	s_mul_i32 s21, s18, s21
	s_sub_i32 s19, s19, s21
	s_add_i32 s20, s20, s19

; __device__ __forceinline__ int lane_id_() { int r; asm volatile("v_mbcnt_lo_u32_b32 %0, -1, 0\n\tv_mbcnt_hi_u32_b32 %0, -1, %0" : "=v"(r)); return r; }
;     __host__ __device__ bool next(int i, Unit& u) const {
;         const long L = (long)i * G + c; if (L >= nwg) return false;
;         int wgid = (int)L; { const int q = nwg / NXCD, r = nwg % NXCD, xcd = wgid % NXCD, off = wgid / NXCD; wgid = (xcd < r ? xcd * (q + 1) : r * (q + 1) + (xcd - r) * q) + off; }
;         const int nig = WGM * nN, gid = wgid / nig, fm = gid * WGM, gsz = (nM - fm) < WGM ? (nM - fm) : WGM;
;         u.pm = fm + ((wgid % nig) % gsz); u.pn = (wgid % nig) / gsz; return true;
;     }
; template <class Epi, class Sched, bool ALIGN_EPI = false, bool SP2 = false>
; __device__ __forceinline__ void gemm_phase(PG8_LAS unsigned char* lds, const Gemm g, const Sched& S, const Epi& E) {
;     int tid_o = S.wv * 64 + lane_id_(); asm volatile("" : "+v"(tid_o));
;     const int tid = tid_o, wid = __builtin_amdgcn_readfirstlane(tid >> 6), lane = tid & 63, wr = wid >> 2, wc = wid & 3, fr = lane & 15, fq = lane >> 4;
.LBB0_1294:
	s_cmp_lt_i32 s82, 7
	s_cselect_b64 s[44:45], -1, 0
	s_and_b64 s[0:1], s[44:45], s[0:1]
	s_andn2_b64 vcc, exec, s[0:1]
	v_writelane_b32 v255, s75, 44
	s_cbranch_vccnz .LBB0_1358
	v_readlane_b32 s3, v254, 10
	s_cmpk_lt_i32 s2, 0xb16
	v_mbcnt_lo_u32_b32 v0, -1, 0
	v_mbcnt_hi_u32_b32 v0, -1, v0
	s_cselect_b64 s[0:1], -1, 0
	v_add_u32_e32 v18, s3, v0
	s_cmpk_gt_i32 s2, 0xb15
	s_nop 0
	v_readfirstlane_b32 s6, v18
	s_cbranch_scc1 .LBB0_1297
	s_ashr_i32 s3, s2, 31
	s_lshr_b32 s3, s3, 29
	s_add_i32 s3, s2, s3
	s_and_b32 s4, s3, -8
	s_sub_i32 s4, s2, s4
	s_mul_i32 s7, s4, 0x162
	s_add_i32 s7, s7, 6
	s_ashr_i32 s3, s3, 3
	s_mul_i32 s5, s4, 0x163
	s_cmp_lt_i32 s4, 6
	s_cselect_b32 s4, s5, s7
	s_add_i32 s4, s4, s3
	s_mul_hi_i32 s3, s4, 0x2fa0be83
	s_lshr_b32 s5, s3, 31
	s_ashr_i32 s3, s3, 6
	s_add_i32 s3, s3, s5
	s_min_i32 s3, s3, 7
	s_lshl_b32 s7, s3, 2
	s_sub_i32 s5, 33, s7
	s_mulk_i32 s3, 0x158
	s_cmp_eq_u32 s5, 5
	s_cselect_b32 s8, 5, 4
	s_sub_i32 s3, s4, s3
	s_sext_i32_i16 s4, s3
	s_waitcnt lgkmcnt(0)
	v_cvt_f32_ubyte0_e32 v1, s8
	v_cvt_f32_i32_e32 v0, s4
	v_rcp_iflag_f32_e32 v2, v1
	s_ashr_i32 s4, s4, 30
	s_or_b32 s9, s4, 1
	v_mul_f32_e32 v2, v0, v2
	v_trunc_f32_e32 v2, v2
	v_fma_f32 v0, -v2, v1, v0
	v_cvt_i32_f32_e32 v2, v2
	v_cmp_ge_f32_e64 s[4:5], |v0|, v1
	s_and_b64 s[4:5], s[4:5], exec
	s_cselect_b32 s4, s9, 0
	v_readfirstlane_b32 s5, v2
	s_add_i32 s4, s5, s4
	s_sext_i32_i16 s90, s4
	s_mul_i32 s4, s4, s8
	s_sub_i32 s3, s3, s4
	s_sext_i32_i16 s3, s3
	s_add_i32 s88, s7, s3

;     __host__ __device__ bool next(int i, Unit& u) const {
;         const long L = (long)i * G + c; if (L >= nwg) return false;
;         int wgid = (int)L; { const int q = nwg / NXCD, r = nwg % NXCD, xcd = wgid % NXCD, off = wgid / NXCD; wgid = (xcd < r ? xcd * (q + 1) : r * (q + 1) + (xcd - r) * q) + off; }
;         const int nig = WGM * nN, gid = wgid / nig, fm = gid * WGM, gsz = (nM - fm) < WGM ? (nM - fm) : WGM;
;         u.pm = fm + ((wgid % nig) % gsz); u.pn = (wgid % nig) / gsz; return true;
;     }
.LBB0_1308:
	s_ashr_i32 s6, s38, 3
	s_add_i32 s6, s40, s6
	s_mul_hi_i32 s7, s6, 0x2fa0be83
	s_lshr_b32 s38, s7, 31
	s_ashr_i32 s7, s7, 6
	s_add_i32 s7, s7, s38
	s_min_i32 s7, s7, 7
	s_lshl_b32 s39, s7, 2
	s_sub_i32 s38, 33, s39
	s_cmp_eq_u32 s38, 5
	s_cselect_b32 s40, 5, 4
	s_abs_i32 s38, s40
	v_cvt_f32_u32_e32 v0, s38
	s_sub_i32 s52, 0, s38
	s_mulk_i32 s7, 0x158
	s_sub_i32 s6, s6, s7
	v_rcp_iflag_f32_e32 v0, v0
	s_abs_i32 s7, s6
	s_xor_b32 s41, s6, s40
	s_ashr_i32 s41, s41, 31
	v_mul_f32_e32 v0, 0x4f7ffffe, v0
	v_cvt_u32_f32_e32 v0, v0
	s_nop 0
	v_readfirstlane_b32 s53, v0
	s_mul_i32 s52, s52, s53
	s_mul_hi_u32 s52, s53, s52
	s_add_i32 s53, s53, s52
	s_mul_hi_u32 s52, s7, s53
	s_mul_i32 s53, s52, s38
	s_sub_i32 s7, s7, s53
	s_add_i32 s69, s52, 1
	s_sub_i32 s53, s7, s38
	s_cmp_ge_u32 s7, s38
	s_cselect_b32 s52, s69, s52
	s_cselect_b32 s7, s53, s7
	s_add_i32 s53, s52, 1
	s_cmp_ge_u32 s7, s38
	s_cselect_b32 s7, s53, s52
	s_xor_b32 s7, s7, s41
	s_sub_i32 s38, s7, s41
	s_mul_i32 s7, s38, s40
	s_sub_i32 s6, s6, s7
	s_add_i32 s40, s39, s6

;     __host__ __device__ bool next(int i, Unit& u) const {
;         const long L = (long)i * G + c; if (L >= nwg) return false;
;         int wgid = (int)L; { const int q = nwg / NXCD, r = nwg % NXCD, xcd = wgid % NXCD, off = wgid / NXCD; wgid = (xcd < r ? xcd * (q + 1) : r * (q + 1) + (xcd - r) * q) + off; }
;         const int nig = WGM * nN, gid = wgid / nig, fm = gid * WGM, gsz = (nM - fm) < WGM ? (nM - fm) : WGM;
;         u.pm = fm + ((wgid % nig) % gsz); u.pn = (wgid % nig) / gsz; return true;
;     }
; template <class Epi, class Sched, bool ALIGN_EPI = false, bool SP2 = false>
; __device__ __forceinline__ void gemm_phase(PG8_LAS unsigned char* lds, const Gemm g, const Sched& S, const Epi& E) {
;     int tid_o = S.wv * 64 + lane_id_(); asm volatile("" : "+v"(tid_o));
;     const int tid = tid_o, wid = __builtin_amdgcn_readfirstlane(tid >> 6), lane = tid & 63, wr = wid >> 2, wc = wid & 3, fr = lane & 15, fq = lane >> 4;
;     const int K = g.K, nt = K / BK;
;     unsigned voffA[2], voffB[2];
; #pragma unroll
;     for (int i = 0; i < 2; ++i) { int R, C; stage_rc(tid * 16 + i * 8192, R, C); const int Rb = Epi::PERM ? ((R & ~31) + perm32(R & 31)) : R;
;         const int Ra = Epi::ROWPERM ? ((R & ~63) + 4 * (R & 15) + ((R >> 4) & 3)) : R;
;         voffA[i] = (unsigned)(Ra * (Epi::ATILED ? BK : K) + C) * 2u; voffB[i] = (unsigned)(Rb * K + C) * 2u; }
;     const size_t kstep = (size_t)(BK * 2);
;     const size_t hstep = (size_t)HALF * K * 2;
;     const size_t tstep = 2 * hstep;
;     const size_t kstepA = Epi::ATILED ? (size_t)(BM * BK * 2) : kstep, hstepA = Epi::ATILED ? (size_t)(HALF * BK * 2) : hstep;
;     const unsigned ldsw = (unsigned)wid * 1024u;
;     const int aoff = lds_byte(wr * 64 + fr, fq * 8), boff = lds_byte(wc * 32 + fr, fq * 8);
;     ...
;     Unit cur, nxt; int ui = 0;
;     if (!S.next(0, cur)) return;
;     f32x4 acc[2][2][4][2];
; #pragma unroll
;     for (int a = 0; a < 2; ++a)
; #pragma unroll
;         for (int b = 0; b < 2; ++b)
; #pragma unroll
;             for (int m = 0; m < 4; ++m)
; #pragma unroll
;                 for (int n = 0; n < 2; ++n) acc[a][b][m][n] = (f32x4){0.f, 0.f, 0.f, 0.f};
;     bf16x8 At[4][2], B0[2][2], B1[2][2];
;     const char* cA = (const char*)g.A + (size_t)cur.pm * tstep; const char* cB = (const char*)g.Bt + (size_t)cur.pn * tstep;
;     S.a_ready(cur);
;     if constexpr (SP2) {
.LBB0_1727:
	s_cmp_lt_i32 s82, 11
	s_cselect_b64 s[4:5], -1, 0
	s_and_b64 s[0:1], s[4:5], s[0:1]
	s_andn2_b64 vcc, exec, s[0:1]
	s_cbranch_vccnz .LBB0_1766
	v_readlane_b32 s0, v254, 10
	v_readlane_b32 s2, v255, 42
	v_mbcnt_lo_u32_b32 v0, -1, 0
	v_mbcnt_hi_u32_b32 v0, -1, v0
	s_cmpk_gt_i32 s2, 0x7dc
	v_add_u32_e32 v14, s0, v0
	v_readlane_b32 s3, v255, 43
	v_readfirstlane_b32 s1, v14
	s_cbranch_scc1 .LBB0_1754
	v_lshlrev_b32_e32 v0, 4, v14
	s_waitcnt lgkmcnt(0)
	v_add_u32_e32 v1, 0x2000, v0
	v_ashrrev_i32_e32 v2, 31, v1
	v_lshrrev_b32_e32 v2, 22, v2
	v_add_u32_e32 v2, v1, v2
	v_ashrrev_i32_e32 v8, 10, v2
	v_mul_i32_i24_e32 v2, 0x400, v8
	v_sub_u32_e32 v1, v1, v2
	v_lshrrev_b32_e32 v2, 4, v1
	v_bitop3_b32 v1, v2, v1, 32 bitop3:0x6c
	v_ashrrev_i32_e32 v2, 31, v1
	v_lshrrev_b32_e32 v2, 26, v2
	v_add_u32_e32 v2, v1, v2
	v_lshlrev_b32_e32 v3, 3, v8
	v_ashrrev_i32_e32 v9, 6, v2
	v_and_b32_e32 v3, -16, v3
	v_add_u32_e32 v3, v9, v3
	v_and_b32_e32 v4, 3, v9
	s_mov_b32 s0, 0x7ffe0
	v_lshrrev_b32_e32 v5, 2, v3
	v_lshlrev_b32_e32 v6, 1, v3
	v_and_b32_e32 v2, 0xc0, v2
	v_and_or_b32 v4, v3, s0, v4
	v_and_b32_e32 v5, 4, v5
	v_and_b32_e32 v6, 24, v6
	v_sub_u32_e32 v1, v1, v2
	v_mov_b32_e32 v2, 1
	v_or3_b32 v4, v4, v5, v6
	v_lshlrev_b32_e32 v5, 5, v8
	v_ashrrev_i16_sdwa v1, v2, sext(v1) dst_sel:DWORD dst_unused:UNUSED_PAD src0_sel:DWORD src1_sel:BYTE_0
	v_and_b32_e32 v5, 32, v5
	v_bfe_i32 v10, v1, 0, 16
	v_add_lshl_u32 v1, v5, v10, 1
	v_lshl_add_u32 v128, v4, 13, v1
	v_lshl_add_u32 v130, v3, 13, v1
	v_bfe_i32 v1, v14, 27, 1
	v_lshrrev_b32_e32 v1, 22, v1
	v_add_u32_e32 v1, v0, v1
	v_and_b32_e32 v1, 0xfffffc00, v1
	v_sub_u32_e32 v0, v0, v1
	v_lshrrev_b32_e32 v1, 4, v0
	v_ashrrev_i32_e32 v3, 31, v14
	v_bitop3_b32 v0, v1, v0, 32 bitop3:0x6c
	v_lshrrev_b32_e32 v3, 26, v3
	v_ashrrev_i32_e32 v1, 31, v0
	v_add_u32_e32 v3, v14, v3
	v_lshrrev_b32_e32 v1, 26, v1
	v_ashrrev_i32_e32 v12, 6, v3
	v_add_u32_e32 v1, v0, v1
	v_lshlrev_b32_e32 v3, 3, v12
	s_add_u32 s3, s80, 0x7b00000
	v_ashrrev_i32_e32 v11, 6, v1
	v_and_b32_e32 v3, -16, v3
	s_addc_u32 s29, s81, 0
	v_add_u32_e32 v3, v11, v3
	v_and_b32_e32 v4, 3, v11
	s_ashr_i32 s52, s2, 31
	v_and_or_b32 v4, v3, s0, v4
	s_lshr_b32 s0, s52, 29
	s_add_i32 s0, s2, s0
	s_and_b32 s6, s0, -8
	s_sub_i32 s6, s2, s6
	s_ashr_i32 s13, s1, 6
	s_mul_i32 s8, s6, 0xfb
	s_ashr_i32 s12, s1, 8
	s_lshl_b32 s33, s13, 10
	s_add_i32 s8, s8, 5
	s_ashr_i32 s0, s0, 3
	s_mul_i32 s7, s6, 0xfc
	s_cmp_lt_i32 s6, 5
	s_cselect_b32 s6, s7, s8
	s_add_i32 s6, s6, s0
	s_mul_hi_i32 s0, s6, 0x4325c53f
	s_lshr_b32 s7, s0, 31
	s_ashr_i32 s0, s0, 6
	v_lshrrev_b32_e32 v5, 2, v3
	v_lshlrev_b32_e32 v6, 1, v3
	v_and_b32_e32 v1, 0xc0, v1
	s_add_i32 s0, s0, s7
	s_min_i32 s0, s0, 7
	v_and_b32_e32 v5, 4, v5
	v_and_b32_e32 v6, 24, v6
	v_sub_u32_e32 v0, v0, v1
	s_lshl_b32 s8, s0, 2
	v_or3_b32 v4, v4, v5, v6
	v_lshlrev_b32_e32 v5, 5, v12
	v_ashrrev_i16_sdwa v0, v2, sext(v0) dst_sel:DWORD dst_unused:UNUSED_PAD src0_sel:DWORD src1_sel:BYTE_0
	s_sub_i32 s7, 33, s8
	s_mulk_i32 s0, 0xf4
	v_and_b32_e32 v5, 32, v5
	v_bfe_i32 v13, v0, 0, 16
	s_cmp_eq_u32 s7, 5
	s_cselect_b32 s9, 5, 4
	s_sub_i32 s10, s6, s0
	v_add_lshl_u32 v0, v5, v13, 1
	s_sext_i32_i16 s0, s10
	v_cvt_f32_ubyte0_e32 v2, s9
	v_lshl_add_u32 v132, v4, 13, v0
	v_cvt_f32_i32_e32 v1, s0
	v_rcp_iflag_f32_e32 v4, v2
	v_lshl_add_u32 v134, v3, 13, v0
	s_ashr_i32 s0, s0, 30
	s_or_b32 s0, s0, 1
	v_mul_f32_e32 v0, v1, v4
	v_trunc_f32_e32 v0, v0
	v_fma_f32 v1, -v0, v2, v1
	v_cvt_i32_f32_e32 v0, v0
	v_cmp_ge_f32_e64 s[6:7], |v1|, v2
	s_and_b64 s[6:7], s[6:7], exec
	s_cselect_b32 s0, s0, 0
	v_readfirstlane_b32 s6, v0
	s_add_i32 s0, s6, s0
	s_mul_i32 s6, s0, s9
	s_sub_i32 s6, s10, s6
	s_sext_i32_i16 s6, s6
	s_add_i32 s30, s8, s6
	s_ashr_i32 s31, s30, 31
	s_bfe_i64 s[8:9], s[0:1], 0x100000
	s_lshl_b64 s[6:7], s[30:31], 21
	s_lshl_b64 s[8:9], s[8:9], 21
	s_add_u32 s40, s3, s8
	s_addc_u32 s41, s29, s9
	s_add_i32 s53, s33, 0
	s_add_i32 m0, s53, 0x10000
	v_mov_b32_e32 v137, 0
	global_load_lds_dwordx4 v132, s[40:41]
	s_add_i32 m0, s53, 0x12000
	s_add_u32 s8, s40, 0x100000
	global_load_lds_dwordx4 v128, s[40:41]
	s_addc_u32 s9, s41, 0
	s_add_i32 m0, s53, 0x14000
	v_mov_b32_e32 v133, v137
	global_load_lds_dwordx4 v132, s[8:9]
	s_add_i32 m0, s53, 0x16000
	s_add_u32 s34, s96, s6
	s_addc_u32 s35, s97, s7
	s_add_i32 s54, s53, 0x2000
	global_load_lds_dwordx4 v128, s[8:9]
	s_mov_b32 m0, s53
	s_add_u32 s6, s34, 0x100000
	global_load_lds_dwordx4 v134, s[34:35]
	s_mov_b32 m0, s54
	s_addc_u32 s7, s35, 0
	s_add_i32 s55, s53, 0x4000
	global_load_lds_dwordx4 v130, s[34:35]
	s_mov_b32 m0, s55
	s_add_i32 s56, s53, 0x6000
	global_load_lds_dwordx4 v134, s[6:7]
	s_mov_b32 m0, s56
	v_mov_b32_e32 v129, v137
	global_load_lds_dwordx4 v130, s[6:7]
	v_mov_b32_e32 v135, v137
	v_mov_b32_e32 v131, v137
	s_cmp_eq_u32 s12, 1
	s_mov_b32 s57, 0
	v_lshl_add_u64 v[6:7], s[40:41], 0, v[132:133]
	v_lshl_add_u64 v[4:5], s[40:41], 0, v[128:129]
	v_lshl_add_u64 v[0:1], s[34:35], 0, v[134:135]
	s_cselect_b64 s[6:7], -1, 0
	s_cmp_lg_u32 s12, 1
	v_lshl_add_u64 v[2:3], s[34:35], 0, v[130:131]
	s_cbranch_scc1 .LBB0_1731
	s_barrier

; __device__ __forceinline__ int lane_id_() { int r; asm volatile("v_mbcnt_lo_u32_b32 %0, -1, 0\n\tv_mbcnt_hi_u32_b32 %0, -1, %0" : "=v"(r)); return r; }
;     __host__ __device__ bool next(int i, Unit& u) const {
;         const long L = (long)i * G + c; if (L >= nwg) return false;
;         int wgid = (int)L; { const int q = nwg / NXCD, r = nwg % NXCD, xcd = wgid % NXCD, off = wgid / NXCD; wgid = (xcd < r ? xcd * (q + 1) : r * (q + 1) + (xcd - r) * q) + off; }
;         const int nig = WGM * nN, gid = wgid / nig, fm = gid * WGM, gsz = (nM - fm) < WGM ? (nM - fm) : WGM;
;         u.pm = fm + ((wgid % nig) % gsz); u.pn = (wgid % nig) / gsz; return true;
;     }
; template <class Epi, class Sched, bool ALIGN_EPI = false, bool SP2 = false>
; __device__ __forceinline__ void gemm_phase(PG8_LAS unsigned char* lds, const Gemm g, const Sched& S, const Epi& E) {
;     int tid_o = S.wv * 64 + lane_id_(); asm volatile("" : "+v"(tid_o));
;     const int tid = tid_o, wid = __builtin_amdgcn_readfirstlane(tid >> 6), lane = tid & 63, wr = wid >> 2, wc = wid & 3, fr = lane & 15, fq = lane >> 4;
.LBB0_2866:
	s_cmp_lt_i32 s82, 16
	s_cselect_b64 s[12:13], -1, 0
	s_and_b64 s[0:1], s[12:13], s[0:1]
	s_andn2_b64 vcc, exec, s[0:1]
	s_cbranch_vccnz .LBB0_2930
	v_readlane_b32 s0, v255, 42
	v_readlane_b32 s3, v254, 10
	v_readlane_b32 s1, v255, 43
	s_mov_b32 s2, s0
	s_cmpk_lt_i32 s0, 0xb16
	v_mbcnt_lo_u32_b32 v0, -1, 0
	v_mbcnt_hi_u32_b32 v0, -1, v0
	s_cselect_b64 s[0:1], -1, 0
	v_add_u32_e32 v8, s3, v0
	s_cmpk_gt_i32 s2, 0xb15
	s_nop 0
	v_readfirstlane_b32 s4, v8
	s_cbranch_scc1 .LBB0_2869
	v_readlane_b32 s2, v255, 42
	v_readlane_b32 s3, v255, 43
	s_ashr_i32 s3, s2, 31
	s_lshr_b32 s3, s3, 29
	s_add_i32 s3, s2, s3
	s_and_b32 s5, s3, -8
	s_sub_i32 s5, s2, s5
	s_mul_i32 s7, s5, 0x162
	s_add_i32 s7, s7, 6
	s_ashr_i32 s3, s3, 3
	s_mul_i32 s6, s5, 0x163
	s_cmp_lt_i32 s5, 6
	s_cselect_b32 s5, s6, s7
	s_add_i32 s5, s5, s3
	s_mul_hi_i32 s3, s5, 0x2fa0be83
	s_lshr_b32 s6, s3, 31
	s_ashr_i32 s3, s3, 6
	s_add_i32 s3, s3, s6
	s_min_i32 s3, s3, 7
	s_lshl_b32 s8, s3, 2
	s_sub_i32 s6, 33, s8
	s_mulk_i32 s3, 0x158
	s_cmp_eq_u32 s6, 5
	s_cselect_b32 s9, 5, 4
	s_sub_i32 s3, s5, s3
	s_sext_i32_i16 s5, s3
	s_waitcnt lgkmcnt(0)
	v_cvt_f32_ubyte0_e32 v1, s9
	v_cvt_f32_i32_e32 v0, s5
	v_rcp_iflag_f32_e32 v2, v1
	s_ashr_i32 s5, s5, 30
	s_or_b32 s5, s5, 1
	v_mul_f32_e32 v2, v0, v2
	v_trunc_f32_e32 v2, v2
	v_fma_f32 v0, -v2, v1, v0
	v_cvt_i32_f32_e32 v2, v2
	v_cmp_ge_f32_e64 s[6:7], |v0|, v1
	s_and_b64 s[6:7], s[6:7], exec
	s_cselect_b32 s5, s5, 0
	v_readfirstlane_b32 s6, v2
	s_add_i32 s5, s6, s5
	s_sext_i32_i16 s6, s5
	s_mul_i32 s5, s5, s9
	s_sub_i32 s3, s3, s5
	s_sext_i32_i16 s3, s3
	s_add_i32 s56, s8, s3

;     __host__ __device__ bool next(int i, Unit& u) const {
;         const long L = (long)i * G + c; if (L >= nwg) return false;
;         int wgid = (int)L; { const int q = nwg / NXCD, r = nwg % NXCD, xcd = wgid % NXCD, off = wgid / NXCD; wgid = (xcd < r ? xcd * (q + 1) : r * (q + 1) + (xcd - r) * q) + off; }
;         const int nig = WGM * nN, gid = wgid / nig, fm = gid * WGM, gsz = (nM - fm) < WGM ? (nM - fm) : WGM;
;         u.pm = fm + ((wgid % nig) % gsz); u.pn = (wgid % nig) / gsz; return true;
;     }
.LBB0_2880:
	s_ashr_i32 s7, s7, 3
	s_add_i32 s7, s51, s7
	s_mul_hi_i32 s48, s7, 0x2fa0be83
	s_lshr_b32 s49, s48, 31
	s_ashr_i32 s48, s48, 6
	s_add_i32 s48, s48, s49
	s_min_i32 s48, s48, 7
	s_lshl_b32 s49, s48, 2
	s_sub_i32 s50, 33, s49
	s_cmp_eq_u32 s50, 5
	s_cselect_b32 s50, 5, 4
	s_abs_i32 s51, s50
	v_cvt_f32_u32_e32 v0, s51
	s_sub_i32 s53, 0, s51
	s_mulk_i32 s48, 0x158
	s_sub_i32 s7, s7, s48
	v_rcp_iflag_f32_e32 v0, v0
	s_abs_i32 s48, s7
	s_xor_b32 s52, s7, s50
	s_ashr_i32 s52, s52, 31
	v_mul_f32_e32 v0, 0x4f7ffffe, v0
	v_cvt_u32_f32_e32 v0, v0
	s_nop 0
	v_readfirstlane_b32 s54, v0
	s_mul_i32 s53, s53, s54
	s_mul_hi_u32 s53, s54, s53
	s_add_i32 s54, s54, s53
	s_mul_hi_u32 s53, s48, s54
	s_mul_i32 s54, s53, s51
	s_sub_i32 s48, s48, s54
	s_add_i32 s55, s53, 1
	s_sub_i32 s54, s48, s51
	s_cmp_ge_u32 s48, s51
	s_cselect_b32 s53, s55, s53
	s_cselect_b32 s48, s54, s48
	s_add_i32 s54, s53, 1
	s_cmp_ge_u32 s48, s51
	s_cselect_b32 s48, s54, s53
	s_xor_b32 s48, s48, s52
	s_sub_i32 s48, s48, s52
	s_mul_i32 s50, s48, s50
	s_sub_i32 s7, s7, s50
	s_add_i32 s50, s49, s7
